# combined: reciprocal-multiply SiLU divisions plus DPP group-norm reductions in the post phase
# speedup vs baseline: 1.0047x; 1.0047x over previous
.LBB0_503:
	v_mad_i64_i32 v[4:5], s[0:1], v82, s15, v[8:9]
	v_lshlrev_b64 v[4:5], 1, v[4:5]
	v_lshl_add_u64 v[14:15], s[10:11], 0, v[4:5]
	v_lshl_add_u64 v[4:5], s[12:13], 0, v[4:5]
	global_load_dwordx2 v[16:17], v[14:15], off nt
	global_load_dwordx2 v[22:23], v[4:5], off nt
	v_mov_b64_e32 v[6:7], s[76:77]
	v_mad_i64_i32 v[6:7], s[0:1], v82, s69, v[6:7]
	v_lshlrev_b32_e32 v144, 1, v8
	v_lshl_add_u64 v[6:7], v[6:7], 0, v[144:145]
	s_mov_b64 s[0:1], 0xb9a3000
	v_lshl_add_u64 v[12:13], v[6:7], 0, s[0:1]
	v_add_co_u32_e32 v6, vcc, 0xb9a3000, v6
	s_nop 1
	v_addc_co_u32_e32 v7, vcc, 0, v7, vcc
	global_load_dwordx2 v[34:35], v[6:7], off nt
	global_load_dwordx2 v[24:25], v[14:15], off offset:512 nt
	global_load_dwordx2 v[26:27], v[4:5], off offset:512 nt
	global_load_dwordx2 v[76:77], v[12:13], off offset:512 nt
	global_load_dwordx2 v[28:29], v[14:15], off offset:1024 nt
	global_load_dwordx2 v[30:31], v[4:5], off offset:1024 nt
	global_load_dwordx2 v[62:63], v[12:13], off offset:1024 nt
	global_load_dwordx2 v[32:33], v[14:15], off offset:1536 nt
	global_load_dwordx2 v[38:39], v[4:5], off offset:1536 nt
	global_load_dwordx2 v[56:57], v[12:13], off offset:1536 nt
	global_load_dwordx2 v[40:41], v[14:15], off offset:2048 nt
	global_load_dwordx2 v[46:47], v[4:5], off offset:2048 nt
	global_load_dwordx2 v[42:43], v[12:13], off offset:2048 nt
	global_load_dwordx2 v[48:49], v[14:15], off offset:2560 nt
	global_load_dwordx2 v[50:51], v[4:5], off offset:2560 nt
	global_load_dwordx2 v[36:37], v[12:13], off offset:2560 nt
	global_load_dwordx2 v[52:53], v[14:15], off offset:3072 nt
	global_load_dwordx2 v[54:55], v[4:5], off offset:3072 nt
	global_load_dwordx2 v[20:21], v[12:13], off offset:3072 nt
	s_nop 0
	global_load_dwordx2 v[14:15], v[14:15], off offset:3584 nt
	s_nop 0
	global_load_dwordx2 v[68:69], v[4:5], off offset:3584 nt
	global_load_dwordx2 v[18:19], v[12:13], off offset:3584 nt
	s_waitcnt vmcnt(21)
	v_lshlrev_b32_e32 v98, 16, v34
	v_mul_f32_e32 v100, 0xbfb8aa3b, v98
	v_exp_f32_e32 v100, v100
	v_and_b32_e32 v34, 0xffff0000, v34
	v_lshlrev_b32_e32 v99, 16, v35
	v_and_b32_e32 v35, 0xffff0000, v35
	v_add_f32_e32 v100, 1.0, v100
	v_lshlrev_b32_e32 v4, 16, v16
	v_and_b32_e32 v5, 0xffff0000, v16
	v_lshlrev_b32_e32 v6, 16, v22
	v_and_b32_e32 v7, 0xffff0000, v22
	v_pk_add_f32 v[4:5], v[4:5], v[6:7]
	v_lshlrev_b32_e32 v6, 16, v17
	v_and_b32_e32 v7, 0xffff0000, v17
	v_lshlrev_b32_e32 v12, 16, v23
	v_and_b32_e32 v13, 0xffff0000, v23
	v_pk_add_f32 v[6:7], v[6:7], v[12:13]
	v_add_f32_e32 v12, v4, v5
	v_add_f32_e32 v12, v6, v12
	v_add_f32_e32 v70, v7, v12
	s_waitcnt vmcnt(20)
	v_lshlrev_b32_e32 v12, 16, v24
	v_and_b32_e32 v13, 0xffff0000, v24
	s_waitcnt vmcnt(19)
	v_lshlrev_b32_e32 v16, 16, v26
	v_and_b32_e32 v17, 0xffff0000, v26
	v_pk_add_f32 v[80:81], v[12:13], v[16:17]
	v_lshlrev_b32_e32 v12, 16, v25
	v_and_b32_e32 v13, 0xffff0000, v25
	v_lshlrev_b32_e32 v16, 16, v27
	v_and_b32_e32 v17, 0xffff0000, v27
	v_pk_add_f32 v[78:79], v[12:13], v[16:17]
	v_add_f32_e32 v12, v80, v81
	v_add_f32_e32 v12, v78, v12
	v_add_f32_e32 v26, v79, v12
	s_waitcnt vmcnt(17)
	v_lshlrev_b32_e32 v12, 16, v28
	v_and_b32_e32 v13, 0xffff0000, v28
	s_waitcnt vmcnt(16)
	v_lshlrev_b32_e32 v16, 16, v30
	v_and_b32_e32 v17, 0xffff0000, v30
	v_pk_add_f32 v[64:65], v[12:13], v[16:17]
	v_lshlrev_b32_e32 v12, 16, v29
	v_and_b32_e32 v13, 0xffff0000, v29
	v_lshlrev_b32_e32 v16, 16, v31
	v_and_b32_e32 v17, 0xffff0000, v31
	v_pk_add_f32 v[66:67], v[12:13], v[16:17]
	v_add_f32_e32 v12, v64, v65
	v_add_f32_e32 v12, v66, v12
	v_add_f32_e32 v27, v67, v12
	s_waitcnt vmcnt(14)
	v_lshlrev_b32_e32 v12, 16, v32
	v_and_b32_e32 v13, 0xffff0000, v32
	ds_bpermute_b32 v32, v84, v26
	s_waitcnt vmcnt(13)
	v_lshlrev_b32_e32 v16, 16, v38
	v_and_b32_e32 v17, 0xffff0000, v38
	v_pk_add_f32 v[60:61], v[12:13], v[16:17]
	v_lshlrev_b32_e32 v12, 16, v33
	s_waitcnt lgkmcnt(0)
	v_add_f32_e32 v26, v26, v32
	ds_bpermute_b32 v32, v84, v27
	v_and_b32_e32 v13, 0xffff0000, v33
	v_lshlrev_b32_e32 v16, 16, v39
	v_and_b32_e32 v17, 0xffff0000, v39
	v_pk_add_f32 v[58:59], v[12:13], v[16:17]
	v_add_f32_e32 v12, v60, v61
	v_add_f32_e32 v12, v58, v12
	v_add_f32_e32 v28, v59, v12
	s_waitcnt vmcnt(11)
	v_lshlrev_b32_e32 v12, 16, v40
	v_and_b32_e32 v13, 0xffff0000, v40
	s_waitcnt vmcnt(10)
	v_lshlrev_b32_e32 v16, 16, v46
	v_and_b32_e32 v17, 0xffff0000, v46
	s_waitcnt lgkmcnt(0)
	v_add_f32_e32 v27, v27, v32
	ds_bpermute_b32 v32, v84, v28
	v_pk_add_f32 v[44:45], v[12:13], v[16:17]
	v_lshlrev_b32_e32 v12, 16, v41
	v_and_b32_e32 v13, 0xffff0000, v41
	v_lshlrev_b32_e32 v16, 16, v47
	v_and_b32_e32 v17, 0xffff0000, v47
	v_pk_add_f32 v[46:47], v[12:13], v[16:17]
	v_add_f32_e32 v12, v44, v45
	v_add_f32_e32 v12, v46, v12
	v_add_f32_e32 v29, v47, v12
	s_waitcnt vmcnt(8)
	v_lshlrev_b32_e32 v12, 16, v48
	v_and_b32_e32 v13, 0xffff0000, v48
	s_waitcnt vmcnt(7)
	v_lshlrev_b32_e32 v16, 16, v50
	v_and_b32_e32 v17, 0xffff0000, v50
	s_waitcnt lgkmcnt(0)
	v_add_f32_e32 v28, v28, v32
	ds_bpermute_b32 v32, v84, v29
	v_pk_add_f32 v[40:41], v[12:13], v[16:17]
	v_lshlrev_b32_e32 v12, 16, v49
	v_and_b32_e32 v13, 0xffff0000, v49
	v_lshlrev_b32_e32 v16, 16, v51
	v_and_b32_e32 v17, 0xffff0000, v51
	v_pk_add_f32 v[38:39], v[12:13], v[16:17]
	v_add_f32_e32 v12, v40, v41
	v_add_f32_e32 v12, v38, v12
	v_add_f32_e32 v30, v39, v12
	s_waitcnt vmcnt(5)
	v_lshlrev_b32_e32 v12, 16, v52
	v_and_b32_e32 v13, 0xffff0000, v52
	s_waitcnt vmcnt(4)
	v_lshlrev_b32_e32 v16, 16, v54
	v_and_b32_e32 v17, 0xffff0000, v54
	s_waitcnt lgkmcnt(0)
	v_add_f32_e32 v29, v29, v32
	ds_bpermute_b32 v32, v84, v30
	v_pk_add_f32 v[22:23], v[12:13], v[16:17]
	v_lshlrev_b32_e32 v12, 16, v53
	v_and_b32_e32 v13, 0xffff0000, v53
	v_lshlrev_b32_e32 v16, 16, v55
	v_and_b32_e32 v17, 0xffff0000, v55
	v_pk_add_f32 v[24:25], v[12:13], v[16:17]
	v_add_f32_e32 v12, v22, v23
	v_add_f32_e32 v12, v24, v12
	v_add_f32_e32 v31, v25, v12
	s_waitcnt vmcnt(2)
	v_lshlrev_b32_e32 v12, 16, v14
	v_and_b32_e32 v13, 0xffff0000, v14
	s_waitcnt vmcnt(1)
	v_lshlrev_b32_e32 v16, 16, v68
	v_and_b32_e32 v17, 0xffff0000, v68
	s_waitcnt lgkmcnt(0)
	v_add_f32_e32 v30, v30, v32
	ds_bpermute_b32 v32, v84, v31
	v_pk_add_f32 v[16:17], v[12:13], v[16:17]
	v_lshlrev_b32_e32 v12, 16, v15
	v_and_b32_e32 v13, 0xffff0000, v15
	v_lshlrev_b32_e32 v14, 16, v69
	v_and_b32_e32 v15, 0xffff0000, v69
	v_pk_add_f32 v[14:15], v[12:13], v[14:15]
	v_add_f32_e32 v12, v16, v17
	v_add_f32_e32 v12, v14, v12
	v_add_f32_e32 v12, v15, v12
	ds_bpermute_b32 v13, v84, v70
	s_waitcnt lgkmcnt(0)
	v_add_f32_e32 v31, v31, v32
	ds_bpermute_b32 v32, v84, v12
	s_waitcnt lgkmcnt(0)
	v_add_f32_e32 v13, v70, v13
	s_waitcnt lgkmcnt(0)
	v_add_f32_e32 v12, v12, v32
	ds_bpermute_b32 v32, v85, v13
	s_waitcnt lgkmcnt(0)
	v_add_f32_e32 v13, v13, v32
	ds_bpermute_b32 v32, v85, v26
	s_waitcnt lgkmcnt(0)
	v_add_f32_e32 v26, v26, v32
	ds_bpermute_b32 v32, v85, v27
	v_rcp_f32_e32 v101, v100
	s_nop 0
	v_mul_f32_e32 v98, v98, v101
	v_mul_f32_e32 v100, 0xbfb8aa3b, v34
	v_exp_f32_e32 v100, v100
	s_waitcnt lgkmcnt(0)
	v_add_f32_e32 v27, v27, v32
	ds_bpermute_b32 v32, v85, v28
	v_add_f32_e32 v100, 1.0, v100
	s_waitcnt lgkmcnt(0)
	v_add_f32_e32 v28, v28, v32
	ds_bpermute_b32 v32, v85, v29
	s_waitcnt lgkmcnt(0)
	v_add_f32_e32 v29, v29, v32
	ds_bpermute_b32 v32, v85, v30
	s_waitcnt lgkmcnt(0)
	v_add_f32_e32 v30, v30, v32
	ds_bpermute_b32 v32, v85, v31
	s_waitcnt lgkmcnt(0)
	v_add_f32_e32 v31, v31, v32
	ds_bpermute_b32 v32, v85, v12
	v_rcp_f32_e32 v101, v100
	s_nop 0
	v_mul_f32_e32 v100, v34, v101
	v_mul_f32_e32 v34, 0xbfb8aa3b, v99
	v_exp_f32_e32 v34, v34
	s_waitcnt lgkmcnt(0)
	v_add_f32_e32 v12, v12, v32
	v_add_f32_e32 v34, 1.0, v34
	s_waitcnt lgkmcnt(0)
	s_nop 1
	v_add_f32_dpp v13, v13, v13 row_mirror row_mask:0xf bank_mask:0xf
	s_waitcnt lgkmcnt(0)
	s_nop 1
	v_add_f32_dpp v26, v26, v26 row_mirror row_mask:0xf bank_mask:0xf
	s_waitcnt lgkmcnt(0)
	s_nop 1
	v_add_f32_dpp v27, v27, v27 row_mirror row_mask:0xf bank_mask:0xf
	s_waitcnt lgkmcnt(0)
	s_nop 1
	v_add_f32_dpp v28, v28, v28 row_mirror row_mask:0xf bank_mask:0xf
	v_rcp_f32_e32 v101, v34
	s_nop 0
	v_mul_f32_e32 v99, v99, v101
	v_mul_f32_e32 v34, 0xbfb8aa3b, v35
	v_exp_f32_e32 v34, v34
	s_waitcnt lgkmcnt(0)
	s_nop 1
	v_add_f32_dpp v29, v29, v29 row_mirror row_mask:0xf bank_mask:0xf
	v_add_f32_e32 v34, 1.0, v34
	s_waitcnt lgkmcnt(0)
	s_nop 1
	v_add_f32_dpp v30, v30, v30 row_mirror row_mask:0xf bank_mask:0xf
	s_waitcnt lgkmcnt(0)
	s_nop 1
	v_add_f32_dpp v31, v31, v31 row_mirror row_mask:0xf bank_mask:0xf
	s_waitcnt lgkmcnt(0)
	s_nop 1
	v_add_f32_dpp v12, v12, v12 row_mirror row_mask:0xf bank_mask:0xf
	s_waitcnt lgkmcnt(0)
	s_nop 1
	v_add_f32_dpp v13, v13, v13 row_half_mirror row_mask:0xf bank_mask:0xf
	v_rcp_f32_e32 v101, v34
	s_nop 0
	v_mul_f32_e32 v101, v35, v101
	s_waitcnt lgkmcnt(0)
	s_nop 1
	v_add_f32_dpp v26, v26, v26 row_half_mirror row_mask:0xf bank_mask:0xf
	s_waitcnt lgkmcnt(0)
	s_nop 1
	v_add_f32_dpp v27, v27, v27 row_half_mirror row_mask:0xf bank_mask:0xf
	s_waitcnt lgkmcnt(0)
	s_nop 1
	v_add_f32_dpp v28, v28, v28 row_half_mirror row_mask:0xf bank_mask:0xf
	s_waitcnt lgkmcnt(0)
	s_nop 1
	v_add_f32_dpp v29, v29, v29 row_half_mirror row_mask:0xf bank_mask:0xf
	s_waitcnt lgkmcnt(0)
	s_nop 1
	v_add_f32_dpp v30, v30, v30 row_half_mirror row_mask:0xf bank_mask:0xf
	s_waitcnt lgkmcnt(0)
	s_nop 1
	v_add_f32_dpp v31, v31, v31 row_half_mirror row_mask:0xf bank_mask:0xf
	s_waitcnt lgkmcnt(0)
	s_nop 1
	v_add_f32_dpp v12, v12, v12 row_half_mirror row_mask:0xf bank_mask:0xf
	s_waitcnt lgkmcnt(0)
	s_nop 1
	v_add_f32_dpp v13, v13, v13 quad_perm:[2,3,0,1] row_mask:0xf bank_mask:0xf
	s_waitcnt lgkmcnt(0)
	s_nop 1
	v_add_f32_dpp v26, v26, v26 quad_perm:[2,3,0,1] row_mask:0xf bank_mask:0xf
	s_waitcnt lgkmcnt(0)
	s_nop 1
	v_add_f32_dpp v27, v27, v27 quad_perm:[2,3,0,1] row_mask:0xf bank_mask:0xf
	s_waitcnt lgkmcnt(0)
	s_nop 1
	v_add_f32_dpp v28, v28, v28 quad_perm:[2,3,0,1] row_mask:0xf bank_mask:0xf
	s_waitcnt lgkmcnt(0)
	s_nop 1
	v_add_f32_dpp v29, v29, v29 quad_perm:[2,3,0,1] row_mask:0xf bank_mask:0xf
	s_waitcnt lgkmcnt(0)
	s_nop 1
	v_add_f32_dpp v30, v30, v30 quad_perm:[2,3,0,1] row_mask:0xf bank_mask:0xf
	s_waitcnt lgkmcnt(0)
	s_nop 1
	v_add_f32_dpp v31, v31, v31 quad_perm:[2,3,0,1] row_mask:0xf bank_mask:0xf
	s_waitcnt lgkmcnt(0)
	s_nop 1
	v_add_f32_dpp v12, v12, v12 quad_perm:[2,3,0,1] row_mask:0xf bank_mask:0xf
	s_waitcnt lgkmcnt(0)
	s_nop 1
	v_add_f32_dpp v13, v13, v13 quad_perm:[1,0,3,2] row_mask:0xf bank_mask:0xf
	v_fmamk_f32 v5, v13, 0xbb800000, v5
	v_fmac_f32_e32 v4, 0xbb800000, v13
	v_fmamk_f32 v7, v13, 0xbb800000, v7
	v_fmac_f32_e32 v6, 0xbb800000, v13
	s_waitcnt lgkmcnt(0)
	s_nop 1
	v_add_f32_dpp v26, v26, v26 quad_perm:[1,0,3,2] row_mask:0xf bank_mask:0xf
	v_fmamk_f32 v81, v26, 0xbb800000, v81
	v_fmac_f32_e32 v80, 0xbb800000, v26
	v_pk_mul_f32 v[92:93], v[4:5], v[4:5]
	v_fmamk_f32 v79, v26, 0xbb800000, v79
	v_fmac_f32_e32 v78, 0xbb800000, v26
	v_pk_mul_f32 v[96:97], v[80:81], v[80:81]
	v_pk_mul_f32 v[90:91], v[6:7], v[6:7]
	v_pk_mul_f32 v[94:95], v[78:79], v[78:79]
	v_mov_b32_e32 v34, v96
	v_mov_b32_e32 v35, v92
	v_mov_b32_e32 v92, v97
	v_pk_add_f32 v[34:35], v[34:35], v[92:93]
	v_mov_b32_e32 v92, v94
	v_mov_b32_e32 v93, v90
	v_pk_add_f32 v[34:35], v[92:93], v[34:35]
	v_mov_b32_e32 v90, v95
	v_pk_add_f32 v[34:35], v[90:91], v[34:35]
	ds_bpermute_b32 v91, v84, v35
	ds_bpermute_b32 v90, v84, v34
	s_waitcnt lgkmcnt(0)
	v_pk_add_f32 v[34:35], v[34:35], v[90:91]
	ds_bpermute_b32 v91, v85, v35
	ds_bpermute_b32 v90, v85, v34
	s_waitcnt lgkmcnt(0)
	s_nop 1
	v_add_f32_dpp v27, v27, v27 quad_perm:[1,0,3,2] row_mask:0xf bank_mask:0xf
	v_fmamk_f32 v65, v27, 0xbb800000, v65
	v_fmac_f32_e32 v64, 0xbb800000, v27
	s_waitcnt lgkmcnt(0)
	v_pk_add_f32 v[34:35], v[34:35], v[90:91]
	s_waitcnt lgkmcnt(0)
	s_nop 1
	v_add_f32_dpp v28, v28, v28 quad_perm:[1,0,3,2] row_mask:0xf bank_mask:0xf
	v_fmamk_f32 v61, v28, 0xbb800000, v61
	v_fmac_f32_e32 v60, 0xbb800000, v28
	v_fmamk_f32 v67, v27, 0xbb800000, v67
	s_waitcnt lgkmcnt(0)
	s_nop 1
	v_add_f32_dpp v29, v29, v29 quad_perm:[1,0,3,2] row_mask:0xf bank_mask:0xf
	s_waitcnt lgkmcnt(0)
	s_nop 1
	v_add_f32_dpp v35, v35, v35 row_mirror row_mask:0xf bank_mask:0xf
	v_add_f32_dpp v34, v34, v34 row_mirror row_mask:0xf bank_mask:0xf
	v_fmac_f32_e32 v66, 0xbb800000, v27
	s_waitcnt lgkmcnt(0)
	s_nop 1
	v_add_f32_dpp v30, v30, v30 quad_perm:[1,0,3,2] row_mask:0xf bank_mask:0xf
	v_pk_mul_f32 v[70:71], v[64:65], v[64:65]
	s_waitcnt lgkmcnt(0)
	s_nop 1
	v_add_f32_dpp v35, v35, v35 row_half_mirror row_mask:0xf bank_mask:0xf
	v_add_f32_dpp v34, v34, v34 row_half_mirror row_mask:0xf bank_mask:0xf
	s_waitcnt lgkmcnt(0)
	s_nop 1
	v_add_f32_dpp v31, v31, v31 quad_perm:[1,0,3,2] row_mask:0xf bank_mask:0xf
	v_fmamk_f32 v59, v28, 0xbb800000, v59
	v_fmac_f32_e32 v58, 0xbb800000, v28
	s_waitcnt lgkmcnt(0)
	s_nop 1
	v_add_f32_dpp v35, v35, v35 quad_perm:[2,3,0,1] row_mask:0xf bank_mask:0xf
	v_add_f32_dpp v34, v34, v34 quad_perm:[2,3,0,1] row_mask:0xf bank_mask:0xf
	s_waitcnt lgkmcnt(0)
	s_nop 1
	v_add_f32_dpp v12, v12, v12 quad_perm:[1,0,3,2] row_mask:0xf bank_mask:0xf
	v_fmamk_f32 v17, v12, 0xbb800000, v17
	v_fmac_f32_e32 v16, 0xbb800000, v12
	v_fmamk_f32 v15, v12, 0xbb800000, v15
	v_fmac_f32_e32 v14, 0xbb800000, v12
	v_mad_i64_i32 v[12:13], s[0:1], v82, s70, v[10:11]
	s_mov_b32 s0, 0x358637bd
	s_waitcnt lgkmcnt(0)
	s_nop 1
	v_add_f32_dpp v91, v35, v35 quad_perm:[1,0,3,2] row_mask:0xf bank_mask:0xf
	v_add_f32_dpp v90, v34, v34 quad_perm:[1,0,3,2] row_mask:0xf bank_mask:0xf
	v_mov_b64_e32 v[34:35], s[0:1]
	v_pk_fma_f32 v[90:91], v[90:91], s[34:35], v[34:35] op_sel_hi:[1,0,0]
	v_pk_mul_f32 v[74:75], v[60:61], v[60:61]
	v_mul_f32_e32 v92, 0x4b800000, v91
	v_cmp_gt_f32_e64 s[0:1], s72, v91
	v_cmp_gt_f32_e32 vcc, s72, v90
	v_pk_mul_f32 v[68:69], v[66:67], v[66:67]
	v_cndmask_b32_e64 v91, v91, v92, s[0:1]
	v_rsq_f32_e32 v91, v91
	v_pk_mul_f32 v[72:73], v[58:59], v[58:59]
	v_fmamk_f32 v45, v29, 0xbb800000, v45
	v_fmac_f32_e32 v44, 0xbb800000, v29
	v_mul_f32_e32 v92, 0x45800000, v91
	v_cndmask_b32_e64 v91, v91, v92, s[0:1]
	v_mul_f32_e32 v4, v4, v91
	v_mul_f32_e32 v5, v5, v91
	v_mul_f32_e32 v4, v0, v4
	v_mul_f32_e32 v5, v1, v5
	v_mul_f32_e32 v4, v98, v4
	v_mul_f32_e32 v5, v100, v5
	v_cvt_pk_bf16_f32 v4, v4, v5
	v_mul_f32_e32 v5, v6, v91
	v_mul_f32_e32 v5, v2, v5
	v_mul_f32_e32 v6, v7, v91
	v_mul_f32_e32 v5, v99, v5
	v_mul_f32_e32 v6, v3, v6
	v_mul_f32_e32 v6, v101, v6
	v_cvt_pk_bf16_f32 v5, v5, v6
	global_store_dwordx2 v[12:13], v[4:5], off
	v_mul_f32_e32 v4, 0x4b800000, v90
	v_cndmask_b32_e32 v4, v90, v4, vcc
	v_rsq_f32_e32 v4, v4
	v_lshlrev_b32_e32 v91, 16, v76
	v_and_b32_e32 v76, 0xffff0000, v76
	v_lshlrev_b32_e32 v92, 16, v77
	v_mul_f32_e32 v5, 0x45800000, v4
	v_cndmask_b32_e32 v90, v4, v5, vcc
	ds_read_b128 v[4:7], v83 offset:1024
	v_mul_f32_e32 v80, v80, v90
	v_and_b32_e32 v77, 0xffff0000, v77
	v_fmamk_f32 v41, v30, 0xbb800000, v41
	v_fmac_f32_e32 v40, 0xbb800000, v30
	s_waitcnt lgkmcnt(0)
	v_mul_f32_e32 v4, v80, v4
	v_mul_f32_e32 v80, 0xbfb8aa3b, v91
	v_exp_f32_e32 v80, v80
	v_fmamk_f32 v47, v29, 0xbb800000, v47
	v_fmac_f32_e32 v46, 0xbb800000, v29
	v_pk_mul_f32 v[50:51], v[44:45], v[44:45]
	v_add_f32_e32 v80, 1.0, v80
	v_fmamk_f32 v39, v30, 0xbb800000, v39
	v_fmac_f32_e32 v38, 0xbb800000, v30
	v_pk_mul_f32 v[54:55], v[40:41], v[40:41]
	v_rcp_f32_e32 v93, v80
	s_nop 0
	v_mul_f32_e32 v80, v91, v93
	v_mul_f32_e32 v4, v80, v4
	v_mul_f32_e32 v80, v81, v90
	v_mul_f32_e32 v5, v80, v5
	v_mul_f32_e32 v80, 0xbfb8aa3b, v76
	v_exp_f32_e32 v80, v80
	v_pk_mul_f32 v[48:49], v[46:47], v[46:47]
	v_pk_mul_f32 v[52:53], v[38:39], v[38:39]
	v_fmamk_f32 v23, v31, 0xbb800000, v23
	v_add_f32_e32 v80, 1.0, v80
	v_fmac_f32_e32 v22, 0xbb800000, v31
	v_fmamk_f32 v25, v31, 0xbb800000, v25
	v_fmac_f32_e32 v24, 0xbb800000, v31
	v_rcp_f32_e32 v81, v80
	s_nop 0
	v_mul_f32_e32 v76, v76, v81
	v_mul_f32_e32 v5, v76, v5
	v_cvt_pk_bf16_f32 v4, v4, v5
	v_mul_f32_e32 v5, v78, v90
	v_mul_f32_e32 v5, v5, v6
	v_mul_f32_e32 v6, 0xbfb8aa3b, v92
	v_exp_f32_e32 v6, v6
	v_pk_mul_f32 v[28:29], v[22:23], v[22:23]
	v_pk_mul_f32 v[32:33], v[16:17], v[16:17]
	v_pk_mul_f32 v[26:27], v[24:25], v[24:25]
	v_add_f32_e32 v6, 1.0, v6
	v_pk_mul_f32 v[30:31], v[14:15], v[14:15]
	v_add_u32_e32 v82, s14, v82
	v_rcp_f32_e32 v76, v6
	s_nop 0
	v_mul_f32_e32 v6, v92, v76
	v_mul_f32_e32 v5, v6, v5
	v_mul_f32_e32 v6, v79, v90
	v_mul_f32_e32 v6, v6, v7
	v_mul_f32_e32 v7, 0xbfb8aa3b, v77
	v_exp_f32_e32 v7, v7
	s_nop 0
	v_add_f32_e32 v7, 1.0, v7
	s_nop 0
	v_rcp_f32_e32 v76, v7
	s_nop 0
	v_mul_f32_e32 v7, v77, v76
	v_lshlrev_b32_e32 v76, 16, v62
	v_mul_f32_e32 v78, 0xbfb8aa3b, v76
	v_exp_f32_e32 v78, v78
	v_and_b32_e32 v62, 0xffff0000, v62
	v_lshlrev_b32_e32 v77, 16, v63
	v_and_b32_e32 v63, 0xffff0000, v63
	v_add_f32_e32 v78, 1.0, v78
	v_mul_f32_e32 v6, v7, v6
	v_cvt_pk_bf16_f32 v5, v5, v6
	global_store_dwordx2 v[12:13], v[4:5], off offset:512
	v_rcp_f32_e32 v79, v78
	s_nop 0
	v_mul_f32_e32 v76, v76, v79
	v_mul_f32_e32 v78, 0xbfb8aa3b, v62
	v_exp_f32_e32 v78, v78
	ds_read_b128 v[4:7], v83 offset:2048
	v_add_f32_e32 v78, 1.0, v78
	s_nop 0
	v_rcp_f32_e32 v79, v78
	s_nop 0
	v_mul_f32_e32 v78, v62, v79
	v_mul_f32_e32 v62, 0xbfb8aa3b, v77
	v_exp_f32_e32 v62, v62
	s_nop 0
	v_add_f32_e32 v62, 1.0, v62
	s_nop 0
	v_rcp_f32_e32 v79, v62
	s_nop 0
	v_mul_f32_e32 v77, v77, v79
	v_mul_f32_e32 v62, 0xbfb8aa3b, v63
	v_exp_f32_e32 v62, v62
	s_nop 0
	v_add_f32_e32 v62, 1.0, v62
	s_nop 0
	v_rcp_f32_e32 v79, v62
	s_nop 0
	v_mul_f32_e32 v79, v63, v79
	v_mov_b32_e32 v62, v74
	v_mov_b32_e32 v63, v70
	v_mov_b32_e32 v70, v75
	v_pk_add_f32 v[62:63], v[62:63], v[70:71]
	v_mov_b32_e32 v70, v72
	v_mov_b32_e32 v71, v68
	v_pk_add_f32 v[62:63], v[70:71], v[62:63]
	v_mov_b32_e32 v68, v73
	v_pk_add_f32 v[62:63], v[68:69], v[62:63]
	ds_bpermute_b32 v69, v84, v63
	ds_bpermute_b32 v68, v84, v62
	s_waitcnt lgkmcnt(0)
	v_pk_add_f32 v[62:63], v[62:63], v[68:69]
	ds_bpermute_b32 v69, v85, v63
	ds_bpermute_b32 v68, v85, v62
	s_waitcnt lgkmcnt(0)
	v_pk_add_f32 v[62:63], v[62:63], v[68:69]
	s_waitcnt lgkmcnt(0)
	s_nop 1
	v_add_f32_dpp v63, v63, v63 row_mirror row_mask:0xf bank_mask:0xf
	v_add_f32_dpp v62, v62, v62 row_mirror row_mask:0xf bank_mask:0xf
	s_waitcnt lgkmcnt(0)
	s_nop 1
	v_add_f32_dpp v63, v63, v63 row_half_mirror row_mask:0xf bank_mask:0xf
	v_add_f32_dpp v62, v62, v62 row_half_mirror row_mask:0xf bank_mask:0xf
	s_waitcnt lgkmcnt(0)
	s_nop 1
	v_add_f32_dpp v63, v63, v63 quad_perm:[2,3,0,1] row_mask:0xf bank_mask:0xf
	v_add_f32_dpp v62, v62, v62 quad_perm:[2,3,0,1] row_mask:0xf bank_mask:0xf
	s_waitcnt lgkmcnt(0)
	s_nop 1
	v_add_f32_dpp v63, v63, v63 quad_perm:[1,0,3,2] row_mask:0xf bank_mask:0xf
	v_add_f32_dpp v62, v62, v62 quad_perm:[1,0,3,2] row_mask:0xf bank_mask:0xf
	s_nop 0
	v_pk_fma_f32 v[62:63], v[62:63], s[34:35], v[34:35] op_sel_hi:[1,0,0]
	s_nop 0
	v_mul_f32_e32 v68, 0x4b800000, v63
	v_cmp_gt_f32_e64 s[0:1], s72, v63
	v_cmp_gt_f32_e32 vcc, s72, v62
	s_nop 0
	v_cndmask_b32_e64 v63, v63, v68, s[0:1]
	v_rsq_f32_e32 v63, v63
	s_nop 0
	v_mul_f32_e32 v68, 0x45800000, v63
	v_cndmask_b32_e64 v63, v63, v68, s[0:1]
	v_mul_f32_e32 v64, v64, v63
	v_mul_f32_e32 v4, v64, v4
	v_mul_f32_e32 v64, v65, v63
	v_mul_f32_e32 v5, v64, v5
	v_mul_f32_e32 v4, v76, v4
	v_mul_f32_e32 v5, v78, v5
	v_cvt_pk_bf16_f32 v4, v4, v5
	v_mul_f32_e32 v5, v66, v63
	v_mul_f32_e32 v5, v5, v6
	v_mul_f32_e32 v6, v67, v63
	v_mul_f32_e32 v5, v77, v5
	v_mul_f32_e32 v6, v6, v7
	v_mul_f32_e32 v6, v79, v6
	v_cvt_pk_bf16_f32 v5, v5, v6
	global_store_dwordx2 v[12:13], v[4:5], off offset:1024
	v_mul_f32_e32 v4, 0x4b800000, v62
	v_cndmask_b32_e32 v4, v62, v4, vcc
	v_rsq_f32_e32 v4, v4
	v_lshlrev_b32_e32 v63, 16, v56
	v_and_b32_e32 v56, 0xffff0000, v56
	v_lshlrev_b32_e32 v64, 16, v57
	v_mul_f32_e32 v5, 0x45800000, v4
	v_cndmask_b32_e32 v62, v4, v5, vcc
	ds_read_b128 v[4:7], v83 offset:3072
	v_mul_f32_e32 v60, v60, v62
	v_and_b32_e32 v57, 0xffff0000, v57
	s_waitcnt lgkmcnt(0)
	v_mul_f32_e32 v4, v60, v4
	v_mul_f32_e32 v60, 0xbfb8aa3b, v63
	v_exp_f32_e32 v60, v60
	s_nop 0
	v_add_f32_e32 v60, 1.0, v60
	s_nop 0
	v_rcp_f32_e32 v65, v60
	s_nop 0
	v_mul_f32_e32 v60, v63, v65
	v_mul_f32_e32 v4, v60, v4
	v_mul_f32_e32 v60, v61, v62
	v_mul_f32_e32 v5, v60, v5
	v_mul_f32_e32 v60, 0xbfb8aa3b, v56
	v_exp_f32_e32 v60, v60
	s_nop 0
	v_add_f32_e32 v60, 1.0, v60
	s_nop 0
	v_rcp_f32_e32 v61, v60
	s_nop 0
	v_mul_f32_e32 v56, v56, v61
	v_mul_f32_e32 v5, v56, v5
	v_cvt_pk_bf16_f32 v4, v4, v5
	v_mul_f32_e32 v5, v58, v62
	v_mul_f32_e32 v5, v5, v6
	v_mul_f32_e32 v6, 0xbfb8aa3b, v64
	v_exp_f32_e32 v6, v6
	s_nop 0
	v_add_f32_e32 v6, 1.0, v6
	s_nop 0
	v_rcp_f32_e32 v56, v6
	s_nop 0
	v_mul_f32_e32 v6, v64, v56
	v_mul_f32_e32 v5, v6, v5
	v_mul_f32_e32 v6, v59, v62
	v_mul_f32_e32 v6, v6, v7
	v_mul_f32_e32 v7, 0xbfb8aa3b, v57
	v_exp_f32_e32 v7, v7
	s_nop 0
	v_add_f32_e32 v7, 1.0, v7
	s_nop 0
	v_rcp_f32_e32 v56, v7
	s_nop 0
	v_mul_f32_e32 v7, v57, v56
	v_lshlrev_b32_e32 v56, 16, v42
	v_mul_f32_e32 v58, 0xbfb8aa3b, v56
	v_exp_f32_e32 v58, v58
	v_and_b32_e32 v42, 0xffff0000, v42
	v_lshlrev_b32_e32 v57, 16, v43
	v_and_b32_e32 v43, 0xffff0000, v43
	v_add_f32_e32 v58, 1.0, v58
	v_mul_f32_e32 v6, v7, v6
	v_cvt_pk_bf16_f32 v5, v5, v6
	global_store_dwordx2 v[12:13], v[4:5], off offset:1536
	v_rcp_f32_e32 v59, v58
	s_nop 0
	v_mul_f32_e32 v56, v56, v59
	v_mul_f32_e32 v58, 0xbfb8aa3b, v42
	v_exp_f32_e32 v58, v58
	ds_read_b128 v[4:7], v83 offset:4096
	v_add_f32_e32 v58, 1.0, v58
	s_nop 0
	v_rcp_f32_e32 v59, v58
	s_nop 0
	v_mul_f32_e32 v58, v42, v59
	v_mul_f32_e32 v42, 0xbfb8aa3b, v57
	v_exp_f32_e32 v42, v42
	s_nop 0
	v_add_f32_e32 v42, 1.0, v42
	s_nop 0
	v_rcp_f32_e32 v59, v42
	s_nop 0
	v_mul_f32_e32 v57, v57, v59
	v_mul_f32_e32 v42, 0xbfb8aa3b, v43
	v_exp_f32_e32 v42, v42
	s_nop 0
	v_add_f32_e32 v42, 1.0, v42
	s_nop 0
	v_rcp_f32_e32 v59, v42
	s_nop 0
	v_mul_f32_e32 v59, v43, v59
	v_mov_b32_e32 v42, v54
	v_mov_b32_e32 v43, v50
	v_mov_b32_e32 v50, v55
	v_pk_add_f32 v[42:43], v[42:43], v[50:51]
	v_mov_b32_e32 v50, v52
	v_mov_b32_e32 v51, v48
	v_pk_add_f32 v[42:43], v[50:51], v[42:43]
	v_mov_b32_e32 v48, v53
	v_pk_add_f32 v[42:43], v[48:49], v[42:43]
	ds_bpermute_b32 v49, v84, v43
	ds_bpermute_b32 v48, v84, v42
	s_waitcnt lgkmcnt(0)
	v_pk_add_f32 v[42:43], v[42:43], v[48:49]
	ds_bpermute_b32 v49, v85, v43
	ds_bpermute_b32 v48, v85, v42
	s_waitcnt lgkmcnt(0)
	v_pk_add_f32 v[42:43], v[42:43], v[48:49]
	s_waitcnt lgkmcnt(0)
	s_nop 1
	v_add_f32_dpp v43, v43, v43 row_mirror row_mask:0xf bank_mask:0xf
	v_add_f32_dpp v42, v42, v42 row_mirror row_mask:0xf bank_mask:0xf
	s_waitcnt lgkmcnt(0)
	s_nop 1
	v_add_f32_dpp v43, v43, v43 row_half_mirror row_mask:0xf bank_mask:0xf
	v_add_f32_dpp v42, v42, v42 row_half_mirror row_mask:0xf bank_mask:0xf
	s_waitcnt lgkmcnt(0)
	s_nop 1
	v_add_f32_dpp v43, v43, v43 quad_perm:[2,3,0,1] row_mask:0xf bank_mask:0xf
	v_add_f32_dpp v42, v42, v42 quad_perm:[2,3,0,1] row_mask:0xf bank_mask:0xf
	s_waitcnt lgkmcnt(0)
	s_nop 1
	v_add_f32_dpp v43, v43, v43 quad_perm:[1,0,3,2] row_mask:0xf bank_mask:0xf
	v_add_f32_dpp v42, v42, v42 quad_perm:[1,0,3,2] row_mask:0xf bank_mask:0xf
	s_nop 0
	v_pk_fma_f32 v[42:43], v[42:43], s[34:35], v[34:35] op_sel_hi:[1,0,0]
	s_nop 0
	v_mul_f32_e32 v48, 0x4b800000, v43
	v_cmp_gt_f32_e64 s[0:1], s72, v43
	v_cmp_gt_f32_e32 vcc, s72, v42
	s_nop 0
	v_cndmask_b32_e64 v43, v43, v48, s[0:1]
	v_rsq_f32_e32 v43, v43
	s_nop 0
	v_mul_f32_e32 v48, 0x45800000, v43
	v_cndmask_b32_e64 v43, v43, v48, s[0:1]
	v_mul_f32_e32 v44, v44, v43
	v_mul_f32_e32 v4, v44, v4
	v_mul_f32_e32 v44, v45, v43
	v_mul_f32_e32 v5, v44, v5
	v_mul_f32_e32 v4, v56, v4
	v_mul_f32_e32 v5, v58, v5
	v_cvt_pk_bf16_f32 v4, v4, v5
	v_mul_f32_e32 v5, v46, v43
	v_mul_f32_e32 v5, v5, v6
	v_mul_f32_e32 v6, v47, v43
	v_mul_f32_e32 v5, v57, v5
	v_mul_f32_e32 v6, v6, v7
	v_mul_f32_e32 v6, v59, v6
	v_cvt_pk_bf16_f32 v5, v5, v6
	global_store_dwordx2 v[12:13], v[4:5], off offset:2048
	v_mul_f32_e32 v4, 0x4b800000, v42
	v_cndmask_b32_e32 v4, v42, v4, vcc
	v_rsq_f32_e32 v4, v4
	v_lshlrev_b32_e32 v43, 16, v36
	v_and_b32_e32 v36, 0xffff0000, v36
	v_lshlrev_b32_e32 v44, 16, v37
	v_mul_f32_e32 v5, 0x45800000, v4
	v_cndmask_b32_e32 v42, v4, v5, vcc
	ds_read_b128 v[4:7], v83 offset:5120
	v_mul_f32_e32 v40, v40, v42
	v_and_b32_e32 v37, 0xffff0000, v37
	s_waitcnt lgkmcnt(0)
	v_mul_f32_e32 v4, v40, v4
	v_mul_f32_e32 v40, 0xbfb8aa3b, v43
	v_exp_f32_e32 v40, v40
	s_nop 0
	v_add_f32_e32 v40, 1.0, v40
	s_nop 0
	v_rcp_f32_e32 v45, v40
	s_nop 0
	v_mul_f32_e32 v40, v43, v45
	v_mul_f32_e32 v4, v40, v4
	v_mul_f32_e32 v40, v41, v42
	v_mul_f32_e32 v5, v40, v5
	v_mul_f32_e32 v40, 0xbfb8aa3b, v36
	v_exp_f32_e32 v40, v40
	s_nop 0
	v_add_f32_e32 v40, 1.0, v40
	s_nop 0
	v_rcp_f32_e32 v41, v40
	s_nop 0
	v_mul_f32_e32 v36, v36, v41
	v_mul_f32_e32 v5, v36, v5
	v_cvt_pk_bf16_f32 v4, v4, v5
	v_mul_f32_e32 v5, v38, v42
	v_mul_f32_e32 v5, v5, v6
	v_mul_f32_e32 v6, 0xbfb8aa3b, v44
	v_exp_f32_e32 v6, v6
	s_nop 0
	v_add_f32_e32 v6, 1.0, v6
	s_nop 0
	v_rcp_f32_e32 v36, v6
	s_nop 0
	v_mul_f32_e32 v6, v44, v36
	v_mul_f32_e32 v5, v6, v5
	v_mul_f32_e32 v6, v39, v42
	v_mul_f32_e32 v6, v6, v7
	v_mul_f32_e32 v7, 0xbfb8aa3b, v37
	v_exp_f32_e32 v7, v7
	s_nop 0
	v_add_f32_e32 v7, 1.0, v7
	s_nop 0
	v_rcp_f32_e32 v36, v7
	s_nop 0
	v_mul_f32_e32 v7, v37, v36
	v_lshlrev_b32_e32 v36, 16, v20
	v_mul_f32_e32 v38, 0xbfb8aa3b, v36
	v_exp_f32_e32 v38, v38
	v_and_b32_e32 v20, 0xffff0000, v20
	v_lshlrev_b32_e32 v37, 16, v21
	v_and_b32_e32 v21, 0xffff0000, v21
	v_add_f32_e32 v38, 1.0, v38
	v_mul_f32_e32 v6, v7, v6
	v_cvt_pk_bf16_f32 v5, v5, v6
	global_store_dwordx2 v[12:13], v[4:5], off offset:2560
	v_rcp_f32_e32 v39, v38
	s_nop 0
	v_mul_f32_e32 v36, v36, v39
	v_mul_f32_e32 v38, 0xbfb8aa3b, v20
	v_exp_f32_e32 v38, v38
	ds_read_b128 v[4:7], v83 offset:6144
	v_add_f32_e32 v38, 1.0, v38
	s_nop 0
	v_rcp_f32_e32 v39, v38
	s_nop 0
	v_mul_f32_e32 v38, v20, v39
	v_mul_f32_e32 v20, 0xbfb8aa3b, v37
	v_exp_f32_e32 v20, v20
	s_nop 0
	v_add_f32_e32 v20, 1.0, v20
	s_nop 0
	v_rcp_f32_e32 v39, v20
	s_nop 0
	v_mul_f32_e32 v37, v37, v39
	v_mul_f32_e32 v20, 0xbfb8aa3b, v21
	v_exp_f32_e32 v20, v20
	s_nop 0
	v_add_f32_e32 v20, 1.0, v20
	s_nop 0
	v_rcp_f32_e32 v39, v20
	s_nop 0
	v_mul_f32_e32 v39, v21, v39
	v_mov_b32_e32 v20, v32
	v_mov_b32_e32 v21, v28
	v_mov_b32_e32 v28, v33
	v_pk_add_f32 v[20:21], v[20:21], v[28:29]
	v_mov_b32_e32 v28, v30
	v_mov_b32_e32 v29, v26
	v_pk_add_f32 v[20:21], v[28:29], v[20:21]
	v_mov_b32_e32 v26, v31
	v_pk_add_f32 v[20:21], v[26:27], v[20:21]
	ds_bpermute_b32 v27, v84, v21
	ds_bpermute_b32 v26, v84, v20
	s_waitcnt lgkmcnt(0)
	v_pk_add_f32 v[20:21], v[20:21], v[26:27]
	ds_bpermute_b32 v27, v85, v21
	ds_bpermute_b32 v26, v85, v20
	s_waitcnt lgkmcnt(0)
	v_pk_add_f32 v[20:21], v[20:21], v[26:27]
	s_waitcnt lgkmcnt(0)
	s_nop 1
	v_add_f32_dpp v21, v21, v21 row_mirror row_mask:0xf bank_mask:0xf
	v_add_f32_dpp v20, v20, v20 row_mirror row_mask:0xf bank_mask:0xf
	s_waitcnt lgkmcnt(0)
	s_nop 1
	v_add_f32_dpp v21, v21, v21 row_half_mirror row_mask:0xf bank_mask:0xf
	v_add_f32_dpp v20, v20, v20 row_half_mirror row_mask:0xf bank_mask:0xf
	s_waitcnt lgkmcnt(0)
	s_nop 1
	v_add_f32_dpp v21, v21, v21 quad_perm:[2,3,0,1] row_mask:0xf bank_mask:0xf
	v_add_f32_dpp v20, v20, v20 quad_perm:[2,3,0,1] row_mask:0xf bank_mask:0xf
	s_waitcnt lgkmcnt(0)
	s_nop 1
	v_add_f32_dpp v21, v21, v21 quad_perm:[1,0,3,2] row_mask:0xf bank_mask:0xf
	v_add_f32_dpp v20, v20, v20 quad_perm:[1,0,3,2] row_mask:0xf bank_mask:0xf
	s_nop 0
	v_pk_fma_f32 v[20:21], v[20:21], s[34:35], v[34:35] op_sel_hi:[1,0,0]
	s_nop 0
	v_mul_f32_e32 v26, 0x4b800000, v21
	v_cmp_gt_f32_e64 s[0:1], s72, v21
	v_cmp_gt_f32_e32 vcc, s72, v20
	s_nop 0
	v_cndmask_b32_e64 v21, v21, v26, s[0:1]
	v_rsq_f32_e32 v21, v21
	s_nop 0
	v_mul_f32_e32 v26, 0x45800000, v21
	v_cndmask_b32_e64 v21, v21, v26, s[0:1]
	v_mul_f32_e32 v22, v22, v21
	v_mul_f32_e32 v4, v22, v4
	v_mul_f32_e32 v22, v23, v21
	v_mul_f32_e32 v5, v22, v5
	v_mul_f32_e32 v4, v36, v4
	v_mul_f32_e32 v5, v38, v5
	v_cvt_pk_bf16_f32 v4, v4, v5
	v_mul_f32_e32 v5, v24, v21
	v_mul_f32_e32 v5, v5, v6
	v_mul_f32_e32 v6, v25, v21
	v_mul_f32_e32 v5, v37, v5
	v_mul_f32_e32 v6, v6, v7
	v_mul_f32_e32 v6, v39, v6
	v_cvt_pk_bf16_f32 v5, v5, v6
	global_store_dwordx2 v[12:13], v[4:5], off offset:3072
	v_mul_f32_e32 v4, 0x4b800000, v20
	v_cndmask_b32_e32 v4, v20, v4, vcc
	v_rsq_f32_e32 v4, v4
	s_waitcnt vmcnt(7)
	v_lshlrev_b32_e32 v21, 16, v18
	v_and_b32_e32 v22, 0xffff0000, v18
	v_lshlrev_b32_e32 v23, 16, v19
	v_mul_f32_e32 v5, 0x45800000, v4
	v_cndmask_b32_e32 v20, v4, v5, vcc
	ds_read_b128 v[4:7], v83 offset:7168
	v_mul_f32_e32 v16, v16, v20
	v_and_b32_e32 v18, 0xffff0000, v19
	s_waitcnt lgkmcnt(0)
	v_mul_f32_e32 v4, v16, v4
	v_mul_f32_e32 v16, 0xbfb8aa3b, v21
	v_exp_f32_e32 v16, v16
	s_nop 0
	v_add_f32_e32 v16, 1.0, v16
	s_nop 0
	v_rcp_f32_e32 v19, v16
	s_nop 0
	v_mul_f32_e32 v16, v21, v19
	v_mul_f32_e32 v4, v16, v4
	v_mul_f32_e32 v16, v17, v20
	v_mul_f32_e32 v5, v16, v5
	v_mul_f32_e32 v16, 0xbfb8aa3b, v22
	v_exp_f32_e32 v16, v16
	s_nop 0
	v_add_f32_e32 v16, 1.0, v16
	s_nop 0
	v_rcp_f32_e32 v17, v16
	s_nop 0
	v_mul_f32_e32 v16, v22, v17
	v_mul_f32_e32 v5, v16, v5
	v_cvt_pk_bf16_f32 v4, v4, v5
	v_mul_f32_e32 v5, v14, v20
	v_mul_f32_e32 v5, v5, v6
	v_mul_f32_e32 v6, 0xbfb8aa3b, v23
	v_exp_f32_e32 v6, v6
	s_nop 0
	v_add_f32_e32 v6, 1.0, v6
	s_nop 0
	v_rcp_f32_e32 v14, v6
	s_nop 0
	v_mul_f32_e32 v6, v23, v14
	v_mul_f32_e32 v5, v6, v5
	v_mul_f32_e32 v6, v15, v20
	v_mul_f32_e32 v6, v6, v7
	v_mul_f32_e32 v7, 0xbfb8aa3b, v18
	v_exp_f32_e32 v7, v7
	s_nop 0
	v_add_f32_e32 v7, 1.0, v7
	s_movk_i32 s0, 0x1fff
	v_cmp_lt_i32_e32 vcc, s0, v82
	v_rcp_f32_e32 v14, v7
	s_nop 0
	v_mul_f32_e32 v7, v18, v14
	s_or_b64 s[6:7], vcc, s[6:7]
	v_mul_f32_e32 v6, v7, v6
	v_cvt_pk_bf16_f32 v5, v5, v6
	global_store_dwordx2 v[12:13], v[4:5], off offset:3584
	s_andn2_b64 exec, exec, s[6:7]
	s_cbranch_execnz .LBB0_503
